# speedup vs baseline: 1.0108x; 1.0025x over previous
; __device__ __forceinline__ KParams kparams() { KParams q = (KParams)__builtin_amdgcn_kernarg_segment_ptr(); asm volatile("" : "+s"(q)); return q; }
; __device__ __forceinline__ int opaque_tid(int wave) { int t = wave * 64 + (int)__builtin_amdgcn_mbcnt_hi(~0u, __builtin_amdgcn_mbcnt_lo(~0u, 0u)); asm volatile("" : "+v"(t)); return t; }
; __device__ __forceinline__ void grid_barrier(unsigned target, const int wave) {
;   asm volatile("s_waitcnt vmcnt(0)" ::: "memory");
;   __syncthreads();
;   if (opaque_tid(wave) == 0) {
;     unsigned* bar = (unsigned*)(kparams()->ws + OFF_BAR);
;     __builtin_amdgcn_fence(__ATOMIC_RELEASE, "agent");
;     asm volatile("s_waitcnt vmcnt(0)" ::: "memory");
;     __hip_atomic_fetch_add(bar, 1u, __ATOMIC_RELAXED, __HIP_MEMORY_SCOPE_AGENT);
;     while (__hip_atomic_load(bar, __ATOMIC_RELAXED, __HIP_MEMORY_SCOPE_AGENT) < target) __builtin_amdgcn_s_sleep(2);
;     __builtin_amdgcn_fence(__ATOMIC_ACQUIRE, "agent");
; __global__ void __launch_bounds__(NTHREADS) mega(Params p) {
;     ...
;     if (ph + 1 < ph1) { ++nbar; grid_barrier(nbar * gridDim.x, wave); }
.Lskip_gbar:
	s_mov_b64 s[4:5], 0
	s_branch .LBB0_18
.LBB0_631:
	s_add_i32 s16, s16, 1
	s_cmp_ge_i32 s16, s17
	s_mov_b64 s[4:5], -1
	s_cbranch_scc1 .LBB0_18
	s_cmp_eq_u32 s16, 7
	s_cbranch_scc1 .Lskip_gbar
	s_cmp_eq_u32 s16, 13
	s_cbranch_scc1 .Lskip_gbar
	s_waitcnt vmcnt(0)
	v_mov_b32_e32 v0, v187
	s_add_i32 s87, s87, 1
	s_waitcnt lgkmcnt(0)
	s_barrier
	s_nop 0
	v_cmp_eq_u32_e32 vcc, 0, v0
	s_and_saveexec_b64 s[4:5], vcc
	s_cbranch_execz .LBB0_17
	s_mov_b64 s[6:7], s[0:1]
	s_load_dword s2, s[20:21], 0x0
	s_load_dwordx2 s[6:7], s[6:7], 0x70
	s_mov_b64 s[8:9], exec
	buffer_wbl2 sc1
	s_waitcnt vmcnt(0) lgkmcnt(0)
	s_waitcnt vmcnt(0)
	v_mbcnt_lo_u32_b32 v0, s8, 0
	s_add_u32 s6, s6, 0x39f80000
	v_mbcnt_hi_u32_b32 v0, s9, v0
	s_addc_u32 s7, s7, 0
	v_cmp_eq_u32_e32 vcc, 0, v0
	s_and_saveexec_b64 s[10:11], vcc
	s_cbranch_execz .LBB0_635
	s_bcnt1_i32_b64 s8, s[8:9]
	v_mov_b32_e32 v0, s8
	global_atomic_add v1, v0, s[6:7]
